# mix0: the second co-resident block of each CU runs gmlp, 4 attention tiles, gmlp (instead of gmlp, gmlp, 4 attention) so every block ends the phase with a short gmlp tile
# speedup vs baseline: 1.0058x; 1.0058x over previous
.LBB0_248:
	s_or_b64 exec, exec, s[0:1]
	s_cmpk_gt_i32 s2, 0xbff
	v_lshlrev_b32_e32 v156, 9, v131
	v_lshlrev_b32_e32 v159, 2, v134
	v_lshlrev_b32_e32 v158, 5, v131
	s_waitcnt lgkmcnt(0)
	s_barrier
	s_cbranch_scc1 .LBB0_261
	v_lshlrev_b32_e32 v4, 13, v135
	v_lshl_add_u32 v6, v134, 3, v138
	v_lshl_or_b32 v8, v134, 11, v4
	v_lshlrev_b32_e32 v10, 5, v138
	v_or3_b32 v77, v4, v137, v10
	v_lshl_or_b32 v102, v6, 2, v8
	v_add_u32_e32 v10, 0x60, v6
	v_add_u32_e32 v6, 0x70, v6
	v_and_b32_e32 v10, 0x7f, v10
	v_and_b32_e32 v6, 0x7f, v6
	v_lshl_or_b32 v103, v10, 2, v8
	v_lshl_or_b32 v104, v6, 2, v8
	v_add_u32_e32 v8, 8, v133
	v_and_b32_e32 v8, 0x78, v8
	v_lshlrev_b32_e32 v6, 9, v136
	v_lshlrev_b32_e32 v8, 2, v8
	v_or3_b32 v106, v4, v6, v8
	v_add_u32_e32 v8, 16, v133
	v_and_b32_e32 v8, 0x78, v8
	v_lshlrev_b32_e32 v6, 9, v132
	v_lshlrev_b32_e32 v8, 2, v8
	v_or3_b32 v108, v4, v6, v8
	v_add_u32_e32 v8, 24, v133
	v_xor_b32_e32 v0, v128, v131
	v_and_b32_e32 v8, 0x78, v8
	v_lshlrev_b32_e32 v1, 3, v0
	v_lshlrev_b32_e32 v6, 9, v130
	v_lshlrev_b32_e32 v8, 2, v8
	v_and_b32_e32 v0, 56, v1
	s_movk_i32 s0, 0x1e0
	v_or3_b32 v110, v4, v6, v8
	v_and_b32_e32 v6, 0x78, v1
	v_xor_b32_e32 v1, 1, v134
	v_and_or_b32 v2, v153, s0, v138
	v_cmp_gt_u32_e64 s[0:1], v1, v134
	v_xor_b32_e32 v1, 2, v134
	v_cmp_gt_u32_e64 s[22:23], v1, v134
	v_xor_b32_e32 v1, 3, v134
	v_cmp_gt_u32_e64 s[4:5], v1, v134
	v_bitop3_b32 v1, v134, v131, 15 bitop3:0x78
	v_lshlrev_b32_e32 v120, 4, v1
	v_bitop3_b32 v1, v134, v138, 4 bitop3:0x36
	v_lshlrev_b32_e32 v121, 4, v1
	v_bitop3_b32 v1, v134, v138, 8 bitop3:0x36
	v_lshlrev_b32_e32 v122, 4, v1
	v_bitop3_b32 v1, v134, v138, 12 bitop3:0x36
	v_lshlrev_b32_e32 v123, 4, v1
	v_xor_b32_e32 v1, v134, v131
	v_lshlrev_b32_e32 v1, 3, v1
	v_and_b32_e32 v124, 0x70, v1
	v_bitop3_b32 v1, v134, v131, 4 bitop3:0x36
	v_lshlrev_b32_e32 v1, 3, v1
	v_and_b32_e32 v125, 0x70, v1
	v_bitop3_b32 v1, v134, v131, 8 bitop3:0x36
	v_lshlrev_b32_e32 v1, 3, v1
	v_and_b32_e32 v126, 0x70, v1
	v_bitop3_b32 v1, v134, v131, 12 bitop3:0x36
	v_mov_b32_e32 v72, 0
	v_lshlrev_b32_e32 v1, 3, v1
	v_and_b32_e32 v127, 0x70, v1
	v_mul_u32_u24_e32 v1, 0x210, v138
	s_movk_i32 s8, 0x2100
	v_and_b32_e32 v10, 0x7f00, v158
	v_mov_b32_e32 v11, v72
	v_mad_u32_u24 v1, v135, s8, v1
	s_movk_i32 s8, 0xfe10
	v_lshl_add_u64 v[12:13], s[50:51], 0, v[10:11]
	v_lshlrev_b32_e32 v14, 1, v0
	v_mov_b32_e32 v15, v72
	s_add_u32 s30, s50, 0x9a00000
	v_lshlrev_b32_e32 v9, 5, v135
	v_mad_i32_i24 v16, v138, s8, v1
	v_lshl_add_u64 v[12:13], v[12:13], 0, v[14:15]
	s_mov_b64 s[8:9], 0x1080000
	v_lshl_add_u64 v[10:11], s[48:49], 0, v[10:11]
	s_addc_u32 s31, s51, 0
	v_bitop3_b32 v3, v128, v139, 3 bitop3:0x6c
	v_or_b32_e32 v4, 16, v9
	v_lshl_add_u64 v[78:79], v[12:13], 0, s[8:9]
	v_lshl_add_u64 v[10:11], v[10:11], 0, v[14:15]
	s_mov_b64 s[8:9], 0x2000000
	s_add_u32 s34, s50, 0xba00000
	v_lshlrev_b32_e32 v75, 7, v138
	v_lshlrev_b32_e32 v3, 4, v3
	v_lshlrev_b32_e32 v5, 7, v2
	v_lshlrev_b32_e32 v7, 4, v152
	v_lshlrev_b32_e32 v2, 3, v138
	v_or_b32_e32 v105, v134, v9
	v_or_b32_e32 v107, v136, v9
	v_or_b32_e32 v109, v132, v9
	v_or_b32_e32 v111, v130, v9
	v_or_b32_e32 v74, v4, v134
	v_or_b32_e32 v112, v136, v4
	v_or_b32_e32 v113, v132, v4
	v_or_b32_e32 v114, v130, v4
	v_lshlrev_b32_e32 v76, 4, v135
	v_lshlrev_b32_e32 v4, 3, v134
	v_and_b32_e32 v8, 0x7f000, v156
	v_mov_b32_e32 v118, 0x10000
	v_and_b32_e32 v9, 48, v131
	v_mul_u32_u24_e32 v17, 0x210, v134
	v_lshl_add_u64 v[80:81], v[10:11], 0, s[8:9]
	s_addc_u32 s35, s51, 0
	v_lshlrev_b32_e32 v10, 1, v6
	v_mov_b32_e32 v11, v72
	v_or_b32_e32 v115, v76, v138
	v_lshlrev_b32_e32 v116, 8, v138
	v_and_b32_e32 v117, 8, v4
	s_mov_b32 s29, 0
	v_cmp_eq_u32_e64 s[6:7], 0, v141
	v_lshl_or_b32 v119, v135, 2, v118
	v_lshl_add_u64 v[82:83], s[34:35], 0, v[10:11]
	s_xor_b32 s33, s2, 63
	s_mov_b64 s[38:39], 0x2000
	v_add_u32_e32 v141, 0x1000, v129
	s_mov_b64 s[46:47], 0x4000
	v_add_u32_e32 v142, 0x2000, v129
	s_mov_b64 s[52:53], 0x6000
	v_add_u32_e32 v143, 0x3000, v129
	v_or_b32_e32 v144, 0x4000, v129
	v_add_u32_e32 v145, 0x5000, v129
	v_add_u32_e32 v146, 0x6000, v129
	v_add_u32_e32 v147, 0x7000, v129
	s_mov_b64 s[56:57], 0x80
	v_or_b32_e32 v148, 0x8000, v129
	s_mov_b64 s[58:59], 0x2080
	v_add_u32_e32 v150, 0x9000, v129
	s_mov_b64 s[60:61], 0x4080
	v_add_u32_e32 v151, 0xa000, v129
	s_mov_b64 s[64:65], 0x6080
	v_add_u32_e32 v160, 0xb000, v129
	v_or_b32_e32 v161, 0xc000, v129
	v_add_u32_e32 v162, 0xd000, v129
	v_add_u32_e32 v163, 0xe000, v129
	v_add_u32_e32 v164, 0xf000, v129
	v_add_u32_e32 v165, v3, v5
	v_add_u32_e32 v166, v3, v75
	v_add_u32_e32 v167, v7, v5
	v_add_u32_e32 v168, v7, v75
	s_movk_i32 s84, 0x7fff
	s_mov_b32 s85, 0x7060302
	v_lshlrev_b32_e32 v84, 1, v4
	v_lshlrev_b32_e32 v86, 1, v6
	s_mov_b64 s[66:67], 0x8000
	s_mov_b64 s[70:71], 0x10000
	s_mov_b64 s[72:73], 0x18000
	v_lshlrev_b32_e32 v88, 1, v8
	v_lshlrev_b32_e32 v90, 1, v0
	s_mov_b64 s[74:75], 0x40000
	s_mov_b64 s[76:77], 0x80000
	s_mov_b64 s[78:79], 0xc0000
	s_mov_b32 s86, 0xc3200000
	v_add_u32_e32 v169, v1, v9
	v_add_u32_e32 v170, v16, v17
	s_mov_b32 s87, 0x5a00000
	v_add_u32_e32 v171, 0x400, v102
	v_lshlrev_b32_e32 v92, 1, v2
	v_mbcnt_hi_u32_b32 v172, -1, v155
	s_mov_b32 s88, s2
	s_and_b32 s98, s2, 0x100
	s_lshl_b32 s98, s98, 3
	s_cmp_eq_u32 s3, 0x200
	s_cselect_b32 s98, s98, 0
	s_add_i32 s88, s88, s98
	s_mov_b32 s99, 0
	s_branch .LBB0_252

.LBB0_251:
	s_sub_i32 s33, s33, s3
	s_cmp_eq_u32 s3, 0x200
	s_cbranch_scc0 .Lmy_m0_lin
	s_add_i32 s99, s99, 1
	s_cmp_ge_u32 s99, 6
	s_cbranch_scc1 .LBB0_261
	s_lshl_b32 s88, s99, 9
	s_add_i32 s88, s88, s2
	s_cmp_eq_u32 s98, 0
	s_cbranch_scc1 .LBB0_252
	s_sub_i32 s88, s88, 0x200
	s_cmp_eq_u32 s99, 5
	s_cselect_b32 s100, 0x200, 0
	s_add_i32 s88, s88, s100
	s_branch .LBB0_252
.Lmy_m0_lin:
	s_add_i32 s88, s88, s3
	s_cmpk_lt_i32 s88, 0xc00
	s_cbranch_scc0 .LBB0_261
